# grid barrier: all waiters (leaders and non-leaders) poll the monotonic TOP counter >= (round+1)*nx instead of release words
# baseline (speedup 1.0000x reference)
.LBB0_82:
	s_or_b64 exec, exec, s[12:13]
	v_cvt_f32_u32_e32 v4, v2
	s_waitcnt vmcnt(0)
	v_readfirstlane_b32 s0, v3
	v_sub_u32_e32 v3, 0, v2
	v_rcp_iflag_f32_e32 v4, v4
	v_add_u32_e32 v5, s0, v1
	v_mul_f32_e32 v4, 0x4f7ffffe, v4
	v_cvt_u32_f32_e32 v4, v4
	v_mul_lo_u32 v1, v3, v4
	v_mul_hi_u32 v1, v4, v1
	v_add_u32_e32 v1, v4, v1
	v_mul_hi_u32 v1, v5, v1
	v_mul_lo_u32 v3, v1, v2
	v_sub_u32_e32 v3, v5, v3
	v_add_u32_e32 v4, 1, v1
	v_cmp_ge_u32_e32 vcc, v3, v2
	s_nop 1
	v_cndmask_b32_e32 v1, v1, v4, vcc
	v_sub_u32_e32 v4, v3, v2
	v_cndmask_b32_e32 v3, v3, v4, vcc
	v_add_u32_e32 v4, 1, v1
	v_cmp_ge_u32_e32 vcc, v3, v2
	v_add_u32_e32 v3, 1, v5
	s_nop 0
	v_cndmask_b32_e32 v1, v1, v4, vcc
	v_mul_lo_u32 v4, v2, v1
	v_add_u32_e32 v2, v4, v2
	v_cmp_ne_u32_e32 vcc, v3, v2
	s_and_saveexec_b64 s[0:1], vcc
	s_xor_b64 s[10:11], exec, s[0:1]
	s_cbranch_execz .LBB0_96
	s_waitcnt lgkmcnt(0)
	v_add_u32_e32 v1, 1, v1
	v_mul_lo_u32 v1, v1, v0
	s_add_u32 s16, s6, 0x32d3400
	s_addc_u32 s17, s7, 0
	v_mov_b32_e32 v0, 0
	global_load_dword v0, v0, s[16:17] sc1
	s_waitcnt vmcnt(0)
	v_cmp_lt_u32_e32 vcc, v0, v1
	s_and_saveexec_b64 s[12:13], vcc
	s_cbranch_execz .LBB0_95
	s_add_u32 s14, s6, 0x32d0200
	s_addc_u32 s15, s7, 0
	s_mov_b32 s0, 1
	s_mov_b64 s[18:19], 0
	v_mov_b32_e32 v0, 0
	s_branch .LBB0_86

.LBB0_90:
	global_load_dword v2, v0, s[16:17] sc1
	s_add_i32 s0, s0, 1
	s_mov_b64 s[28:29], -1
	s_waitcnt vmcnt(0)
	v_cmp_ge_u32_e32 vcc, v2, v1
	s_orn2_b64 s[26:27], vcc, exec
	s_branch .LBB0_85

.LBB0_99:
	s_or_b64 exec, exec, s[12:13]
	v_cvt_f32_u32_e32 v3, v0
	s_waitcnt vmcnt(0)
	v_readfirstlane_b32 s0, v2
	s_add_u32 s12, s6, 0x32d3500
	s_addc_u32 s13, s7, 0
	v_rcp_iflag_f32_e32 v3, v3
	v_add_u32_e32 v1, s0, v1
	v_add_u32_e32 v4, 1, v1
	s_mov_b64 s[14:15], -1
	v_mul_f32_e32 v2, 0x4f7ffffe, v3
	v_cvt_u32_f32_e32 v2, v2
	v_sub_u32_e32 v3, 0, v0
	v_mul_lo_u32 v3, v3, v2
	v_mul_hi_u32 v3, v2, v3
	v_add_u32_e32 v2, v2, v3
	v_mul_hi_u32 v2, v1, v2
	v_mul_lo_u32 v3, v2, v0
	v_sub_u32_e32 v1, v1, v3
	v_add_u32_e32 v5, 1, v2
	v_cmp_ge_u32_e32 vcc, v1, v0
	v_sub_u32_e32 v3, v1, v0
	s_nop 0
	v_cndmask_b32_e32 v2, v2, v5, vcc
	v_cndmask_b32_e32 v1, v1, v3, vcc
	v_add_u32_e32 v3, 1, v2
	v_cmp_ge_u32_e32 vcc, v1, v0
	s_nop 1
	v_cndmask_b32_e32 v2, v2, v3, vcc
	v_mul_lo_u32 v1, v0, v2
	v_add_u32_e32 v0, v1, v0
	v_cmp_ne_u32_e32 vcc, v4, v0
	v_mov_b32_e32 v2, v0
	v_mov_b64_e32 v[0:1], s[12:13]
	s_and_saveexec_b64 s[10:11], vcc
	s_cbranch_execz .LBB0_111
	v_mov_b32_e32 v0, 0
	global_load_dword v1, v0, s[12:13] offset:-256 sc1
	s_mov_b64 s[18:19], 0
	s_waitcnt vmcnt(0)
	v_cmp_lt_u32_e32 vcc, v1, v2
	s_and_saveexec_b64 s[16:17], vcc
	s_cbranch_execz .LBB0_110
	s_add_u32 s14, s6, 0x32d0200
	s_addc_u32 s15, s7, 0
	s_mov_b32 s0, 1
	s_mov_b64 s[6:7], 0
	s_branch .LBB0_103

.LBB0_107:
	global_load_dword v1, v0, s[12:13] offset:-256 sc1
	s_add_i32 s0, s0, 1
	s_mov_b64 s[24:25], -1
	s_waitcnt vmcnt(0)
	v_cmp_ge_u32_e32 vcc, v1, v2
	s_orn2_b64 s[28:29], vcc, exec
	s_branch .LBB0_102

.LBB0_218:
	s_or_b64 exec, exec, s[12:13]
	v_cvt_f32_u32_e32 v4, v2
	s_waitcnt vmcnt(0)
	v_readfirstlane_b32 s0, v3
	v_sub_u32_e32 v3, 0, v2
	v_rcp_iflag_f32_e32 v4, v4
	v_add_u32_e32 v5, s0, v1
	v_mul_f32_e32 v4, 0x4f7ffffe, v4
	v_cvt_u32_f32_e32 v4, v4
	v_mul_lo_u32 v1, v3, v4
	v_mul_hi_u32 v1, v4, v1
	v_add_u32_e32 v1, v4, v1
	v_mul_hi_u32 v1, v5, v1
	v_mul_lo_u32 v3, v1, v2
	v_sub_u32_e32 v3, v5, v3
	v_add_u32_e32 v4, 1, v1
	v_cmp_ge_u32_e32 vcc, v3, v2
	s_nop 1
	v_cndmask_b32_e32 v1, v1, v4, vcc
	v_sub_u32_e32 v4, v3, v2
	v_cndmask_b32_e32 v3, v3, v4, vcc
	v_add_u32_e32 v4, 1, v1
	v_cmp_ge_u32_e32 vcc, v3, v2
	v_add_u32_e32 v3, 1, v5
	s_nop 0
	v_cndmask_b32_e32 v1, v1, v4, vcc
	v_mul_lo_u32 v4, v2, v1
	v_add_u32_e32 v2, v4, v2
	v_cmp_ne_u32_e32 vcc, v3, v2
	s_and_saveexec_b64 s[0:1], vcc
	s_xor_b64 s[8:9], exec, s[0:1]
	s_cbranch_execz .LBB0_232
	s_waitcnt lgkmcnt(0)
	v_add_u32_e32 v1, 1, v1
	v_mul_lo_u32 v1, v1, v0
	s_add_u32 s16, s10, 0x32d3400
	s_addc_u32 s17, s11, 0
	v_mov_b32_e32 v0, 0
	global_load_dword v0, v0, s[16:17] sc1
	s_waitcnt vmcnt(0)
	v_cmp_lt_u32_e32 vcc, v0, v1
	s_and_saveexec_b64 s[12:13], vcc
	s_cbranch_execz .LBB0_231
	s_add_u32 s14, s10, 0x32d0200
	s_addc_u32 s15, s11, 0
	s_mov_b32 s0, 1
	s_mov_b64 s[18:19], 0
	v_mov_b32_e32 v0, 0
	s_branch .LBB0_222

.LBB0_235:
	s_or_b64 exec, exec, s[12:13]
	v_cvt_f32_u32_e32 v3, v0
	s_waitcnt vmcnt(0)
	v_readfirstlane_b32 s0, v2
	s_add_u32 s12, s10, 0x32d3500
	s_addc_u32 s13, s11, 0
	v_rcp_iflag_f32_e32 v3, v3
	v_add_u32_e32 v1, s0, v1
	v_add_u32_e32 v4, 1, v1
	s_mov_b64 s[14:15], -1
	v_mul_f32_e32 v2, 0x4f7ffffe, v3
	v_cvt_u32_f32_e32 v2, v2
	v_sub_u32_e32 v3, 0, v0
	v_mul_lo_u32 v3, v3, v2
	v_mul_hi_u32 v3, v2, v3
	v_add_u32_e32 v2, v2, v3
	v_mul_hi_u32 v2, v1, v2
	v_mul_lo_u32 v3, v2, v0
	v_sub_u32_e32 v1, v1, v3
	v_add_u32_e32 v5, 1, v2
	v_cmp_ge_u32_e32 vcc, v1, v0
	v_sub_u32_e32 v3, v1, v0
	s_nop 0
	v_cndmask_b32_e32 v2, v2, v5, vcc
	v_cndmask_b32_e32 v1, v1, v3, vcc
	v_add_u32_e32 v3, 1, v2
	v_cmp_ge_u32_e32 vcc, v1, v0
	s_nop 1
	v_cndmask_b32_e32 v2, v2, v3, vcc
	v_mul_lo_u32 v1, v0, v2
	v_add_u32_e32 v0, v1, v0
	v_cmp_ne_u32_e32 vcc, v4, v0
	v_mov_b32_e32 v2, v0
	v_mov_b64_e32 v[0:1], s[12:13]
	s_and_saveexec_b64 s[8:9], vcc
	s_cbranch_execz .LBB0_247
	v_mov_b32_e32 v0, 0
	global_load_dword v1, v0, s[12:13] offset:-256 sc1
	s_mov_b64 s[18:19], 0
	s_waitcnt vmcnt(0)
	v_cmp_lt_u32_e32 vcc, v1, v2
	s_and_saveexec_b64 s[16:17], vcc
	s_cbranch_execz .LBB0_246
	s_add_u32 s14, s10, 0x32d0200
	s_addc_u32 s15, s11, 0
	s_mov_b32 s0, 1
	s_mov_b64 s[10:11], 0
	s_branch .LBB0_239

.LBB0_501:
	s_or_b64 exec, exec, s[12:13]
	v_cvt_f32_u32_e32 v4, v2
	s_waitcnt vmcnt(0)
	v_readfirstlane_b32 s1, v3
	v_sub_u32_e32 v3, 0, v2
	v_rcp_iflag_f32_e32 v4, v4
	v_add_u32_e32 v5, s1, v1
	v_mul_f32_e32 v4, 0x4f7ffffe, v4
	v_cvt_u32_f32_e32 v4, v4
	v_mul_lo_u32 v1, v3, v4
	v_mul_hi_u32 v1, v4, v1
	v_add_u32_e32 v1, v4, v1
	v_mul_hi_u32 v1, v5, v1
	v_mul_lo_u32 v3, v1, v2
	v_sub_u32_e32 v3, v5, v3
	v_add_u32_e32 v4, 1, v1
	v_cmp_ge_u32_e32 vcc, v3, v2
	s_nop 1
	v_cndmask_b32_e32 v1, v1, v4, vcc
	v_sub_u32_e32 v4, v3, v2
	v_cndmask_b32_e32 v3, v3, v4, vcc
	v_add_u32_e32 v4, 1, v1
	v_cmp_ge_u32_e32 vcc, v3, v2
	v_add_u32_e32 v3, 1, v5
	s_nop 0
	v_cndmask_b32_e32 v1, v1, v4, vcc
	v_mul_lo_u32 v4, v2, v1
	v_add_u32_e32 v2, v4, v2
	v_cmp_ne_u32_e32 vcc, v3, v2
	s_and_saveexec_b64 s[10:11], vcc
	s_xor_b64 s[10:11], exec, s[10:11]
	s_cbranch_execz .LBB0_515
	s_waitcnt lgkmcnt(0)
	v_add_u32_e32 v1, 1, v1
	v_mul_lo_u32 v1, v1, v0
	s_add_u32 s18, s16, 0x32d3400
	s_addc_u32 s19, s17, 0
	v_mov_b32_e32 v0, 0
	global_load_dword v0, v0, s[18:19] sc1
	s_waitcnt vmcnt(0)
	v_cmp_lt_u32_e32 vcc, v0, v1
	s_and_saveexec_b64 s[12:13], vcc
	s_cbranch_execz .LBB0_514
	s_add_u32 s14, s16, 0x32d0200
	s_addc_u32 s15, s17, 0
	s_mov_b32 s1, 1
	s_mov_b64 s[24:25], 0
	v_mov_b32_e32 v0, 0
	s_branch .LBB0_505

.LBB0_509:
	global_load_dword v2, v0, s[18:19] sc1
	s_add_i32 s1, s1, 1
	s_mov_b64 s[38:39], -1
	s_waitcnt vmcnt(0)
	v_cmp_ge_u32_e32 vcc, v2, v1
	s_orn2_b64 s[36:37], vcc, exec
	s_branch .LBB0_504

.LBB0_518:
	s_or_b64 exec, exec, s[12:13]
	v_cvt_f32_u32_e32 v3, v0
	s_waitcnt vmcnt(0)
	v_readfirstlane_b32 s1, v2
	s_add_u32 s12, s16, 0x32d3500
	s_addc_u32 s13, s17, 0
	v_rcp_iflag_f32_e32 v3, v3
	v_add_u32_e32 v1, s1, v1
	v_add_u32_e32 v4, 1, v1
	s_mov_b64 s[14:15], -1
	v_mul_f32_e32 v2, 0x4f7ffffe, v3
	v_cvt_u32_f32_e32 v2, v2
	v_sub_u32_e32 v3, 0, v0
	v_mul_lo_u32 v3, v3, v2
	v_mul_hi_u32 v3, v2, v3
	v_add_u32_e32 v2, v2, v3
	v_mul_hi_u32 v2, v1, v2
	v_mul_lo_u32 v3, v2, v0
	v_sub_u32_e32 v1, v1, v3
	v_add_u32_e32 v5, 1, v2
	v_cmp_ge_u32_e32 vcc, v1, v0
	v_sub_u32_e32 v3, v1, v0
	s_nop 0
	v_cndmask_b32_e32 v2, v2, v5, vcc
	v_cndmask_b32_e32 v1, v1, v3, vcc
	v_add_u32_e32 v3, 1, v2
	v_cmp_ge_u32_e32 vcc, v1, v0
	s_nop 1
	v_cndmask_b32_e32 v2, v2, v3, vcc
	v_mul_lo_u32 v1, v0, v2
	v_add_u32_e32 v0, v1, v0
	v_cmp_ne_u32_e32 vcc, v4, v0
	v_mov_b32_e32 v2, v0
	v_mov_b64_e32 v[0:1], s[12:13]
	s_and_saveexec_b64 s[10:11], vcc
	s_cbranch_execz .LBB0_530
	v_mov_b32_e32 v0, 0
	global_load_dword v1, v0, s[12:13] offset:-256 sc1
	s_mov_b64 s[24:25], 0
	s_waitcnt vmcnt(0)
	v_cmp_lt_u32_e32 vcc, v1, v2
	s_and_saveexec_b64 s[18:19], vcc
	s_cbranch_execz .LBB0_529
	s_add_u32 s14, s16, 0x32d0200
	s_addc_u32 s15, s17, 0
	s_mov_b32 s1, 1
	s_mov_b64 s[16:17], 0
	s_branch .LBB0_522

.LBB0_526:
	global_load_dword v1, v0, s[12:13] offset:-256 sc1
	s_add_i32 s1, s1, 1
	s_mov_b64 s[26:27], -1
	s_waitcnt vmcnt(0)
	v_cmp_ge_u32_e32 vcc, v1, v2
	s_orn2_b64 s[38:39], vcc, exec
	s_branch .LBB0_521

.LBB0_561:
	s_or_b64 exec, exec, s[14:15]
	v_cvt_f32_u32_e32 v4, v2
	s_waitcnt vmcnt(0)
	v_readfirstlane_b32 s1, v3
	v_sub_u32_e32 v3, 0, v2
	v_rcp_iflag_f32_e32 v4, v4
	v_add_u32_e32 v5, s1, v1
	v_mul_f32_e32 v4, 0x4f7ffffe, v4
	v_cvt_u32_f32_e32 v4, v4
	v_mul_lo_u32 v1, v3, v4
	v_mul_hi_u32 v1, v4, v1
	v_add_u32_e32 v1, v4, v1
	v_mul_hi_u32 v1, v5, v1
	v_mul_lo_u32 v3, v1, v2
	v_sub_u32_e32 v3, v5, v3
	v_add_u32_e32 v4, 1, v1
	v_cmp_ge_u32_e32 vcc, v3, v2
	s_nop 1
	v_cndmask_b32_e32 v1, v1, v4, vcc
	v_sub_u32_e32 v4, v3, v2
	v_cndmask_b32_e32 v3, v3, v4, vcc
	v_add_u32_e32 v4, 1, v1
	v_cmp_ge_u32_e32 vcc, v3, v2
	v_add_u32_e32 v3, 1, v5
	s_nop 0
	v_cndmask_b32_e32 v1, v1, v4, vcc
	v_mul_lo_u32 v4, v2, v1
	v_add_u32_e32 v2, v4, v2
	v_cmp_ne_u32_e32 vcc, v3, v2
	s_and_saveexec_b64 s[12:13], vcc
	s_xor_b64 s[12:13], exec, s[12:13]
	s_cbranch_execz .LBB0_575
	s_waitcnt lgkmcnt(0)
	v_add_u32_e32 v1, 1, v1
	v_mul_lo_u32 v1, v1, v0
	s_add_u32 s18, s6, 0x32d3400
	s_addc_u32 s19, s7, 0
	v_mov_b32_e32 v0, 0
	global_load_dword v0, v0, s[18:19] sc1
	s_waitcnt vmcnt(0)
	v_cmp_lt_u32_e32 vcc, v0, v1
	s_and_saveexec_b64 s[14:15], vcc
	s_cbranch_execz .LBB0_574
	s_add_u32 s16, s6, 0x32d0200
	s_addc_u32 s17, s7, 0
	s_mov_b32 s1, 1
	s_mov_b64 s[24:25], 0
	v_mov_b32_e32 v0, 0
	s_branch .LBB0_565

.LBB0_578:
	s_or_b64 exec, exec, s[14:15]
	v_cvt_f32_u32_e32 v3, v0
	s_waitcnt vmcnt(0)
	v_readfirstlane_b32 s1, v2
	s_add_u32 s14, s6, 0x32d3500
	s_addc_u32 s15, s7, 0
	v_rcp_iflag_f32_e32 v3, v3
	v_add_u32_e32 v1, s1, v1
	v_add_u32_e32 v4, 1, v1
	s_mov_b64 s[16:17], -1
	v_mul_f32_e32 v2, 0x4f7ffffe, v3
	v_cvt_u32_f32_e32 v2, v2
	v_sub_u32_e32 v3, 0, v0
	v_mul_lo_u32 v3, v3, v2
	v_mul_hi_u32 v3, v2, v3
	v_add_u32_e32 v2, v2, v3
	v_mul_hi_u32 v2, v1, v2
	v_mul_lo_u32 v3, v2, v0
	v_sub_u32_e32 v1, v1, v3
	v_add_u32_e32 v5, 1, v2
	v_cmp_ge_u32_e32 vcc, v1, v0
	v_sub_u32_e32 v3, v1, v0
	s_nop 0
	v_cndmask_b32_e32 v2, v2, v5, vcc
	v_cndmask_b32_e32 v1, v1, v3, vcc
	v_add_u32_e32 v3, 1, v2
	v_cmp_ge_u32_e32 vcc, v1, v0
	s_nop 1
	v_cndmask_b32_e32 v2, v2, v3, vcc
	v_mul_lo_u32 v1, v0, v2
	v_add_u32_e32 v0, v1, v0
	v_cmp_ne_u32_e32 vcc, v4, v0
	v_mov_b32_e32 v2, v0
	v_mov_b64_e32 v[0:1], s[14:15]
	s_and_saveexec_b64 s[12:13], vcc
	s_cbranch_execz .LBB0_590
	v_mov_b32_e32 v0, 0
	global_load_dword v1, v0, s[14:15] offset:-256 sc1
	s_mov_b64 s[24:25], 0
	s_waitcnt vmcnt(0)
	v_cmp_lt_u32_e32 vcc, v1, v2
	s_and_saveexec_b64 s[18:19], vcc
	s_cbranch_execz .LBB0_589
	s_add_u32 s16, s6, 0x32d0200
	s_addc_u32 s17, s7, 0
	s_mov_b32 s1, 1
	s_mov_b64 s[6:7], 0
	s_branch .LBB0_582

.LBB0_586:
	global_load_dword v1, v0, s[14:15] offset:-256 sc1
	s_add_i32 s1, s1, 1
	s_mov_b64 s[26:27], -1
	s_waitcnt vmcnt(0)
	v_cmp_ge_u32_e32 vcc, v1, v2
	s_orn2_b64 s[38:39], vcc, exec
	s_branch .LBB0_581

.LBB0_848:
	s_or_b64 exec, exec, s[10:11]
	v_cvt_f32_u32_e32 v4, v2
	s_waitcnt vmcnt(0)
	v_readfirstlane_b32 s0, v3
	v_sub_u32_e32 v3, 0, v2
	v_rcp_iflag_f32_e32 v4, v4
	v_add_u32_e32 v5, s0, v1
	v_mul_f32_e32 v4, 0x4f7ffffe, v4
	v_cvt_u32_f32_e32 v4, v4
	v_mul_lo_u32 v1, v3, v4
	v_mul_hi_u32 v1, v4, v1
	v_add_u32_e32 v1, v4, v1
	v_mul_hi_u32 v1, v5, v1
	v_mul_lo_u32 v3, v1, v2
	v_sub_u32_e32 v3, v5, v3
	v_add_u32_e32 v4, 1, v1
	v_cmp_ge_u32_e32 vcc, v3, v2
	s_nop 1
	v_cndmask_b32_e32 v1, v1, v4, vcc
	v_sub_u32_e32 v4, v3, v2
	v_cndmask_b32_e32 v3, v3, v4, vcc
	v_add_u32_e32 v4, 1, v1
	v_cmp_ge_u32_e32 vcc, v3, v2
	v_add_u32_e32 v3, 1, v5
	s_nop 0
	v_cndmask_b32_e32 v1, v1, v4, vcc
	v_mul_lo_u32 v4, v2, v1
	v_add_u32_e32 v2, v4, v2
	v_cmp_ne_u32_e32 vcc, v3, v2
	s_and_saveexec_b64 s[0:1], vcc
	s_xor_b64 s[8:9], exec, s[0:1]
	s_cbranch_execz .LBB0_862
	s_waitcnt lgkmcnt(0)
	v_add_u32_e32 v1, 1, v1
	v_mul_lo_u32 v1, v1, v0
	s_add_u32 s14, s18, 0x32d3400
	s_addc_u32 s15, s19, 0
	v_mov_b32_e32 v0, 0
	global_load_dword v0, v0, s[14:15] sc1
	s_waitcnt vmcnt(0)
	v_cmp_lt_u32_e32 vcc, v0, v1
	s_and_saveexec_b64 s[10:11], vcc
	s_cbranch_execz .LBB0_861
	s_add_u32 s12, s18, 0x32d0200
	s_addc_u32 s13, s19, 0
	s_mov_b32 s0, 1
	s_mov_b64 s[16:17], 0
	v_mov_b32_e32 v0, 0
	s_branch .LBB0_852

.LBB0_856:
	global_load_dword v2, v0, s[14:15] sc1
	s_add_i32 s0, s0, 1
	s_mov_b64 s[30:31], -1
	s_waitcnt vmcnt(0)
	v_cmp_ge_u32_e32 vcc, v2, v1
	s_orn2_b64 s[26:27], vcc, exec
	s_branch .LBB0_851

.LBB0_865:
	s_or_b64 exec, exec, s[10:11]
	v_cvt_f32_u32_e32 v3, v0
	s_waitcnt vmcnt(0)
	v_readfirstlane_b32 s0, v2
	s_add_u32 s10, s18, 0x32d3500
	s_addc_u32 s11, s19, 0
	v_rcp_iflag_f32_e32 v3, v3
	v_add_u32_e32 v1, s0, v1
	v_add_u32_e32 v4, 1, v1
	s_mov_b64 s[12:13], -1
	v_mul_f32_e32 v2, 0x4f7ffffe, v3
	v_cvt_u32_f32_e32 v2, v2
	v_sub_u32_e32 v3, 0, v0
	v_mul_lo_u32 v3, v3, v2
	v_mul_hi_u32 v3, v2, v3
	v_add_u32_e32 v2, v2, v3
	v_mul_hi_u32 v2, v1, v2
	v_mul_lo_u32 v3, v2, v0
	v_sub_u32_e32 v1, v1, v3
	v_add_u32_e32 v5, 1, v2
	v_cmp_ge_u32_e32 vcc, v1, v0
	v_sub_u32_e32 v3, v1, v0
	s_nop 0
	v_cndmask_b32_e32 v2, v2, v5, vcc
	v_cndmask_b32_e32 v1, v1, v3, vcc
	v_add_u32_e32 v3, 1, v2
	v_cmp_ge_u32_e32 vcc, v1, v0
	s_nop 1
	v_cndmask_b32_e32 v2, v2, v3, vcc
	v_mul_lo_u32 v1, v0, v2
	v_add_u32_e32 v0, v1, v0
	v_cmp_ne_u32_e32 vcc, v4, v0
	v_mov_b32_e32 v2, v0
	v_mov_b64_e32 v[0:1], s[10:11]
	s_and_saveexec_b64 s[8:9], vcc
	s_cbranch_execz .LBB0_877
	v_mov_b32_e32 v0, 0
	global_load_dword v1, v0, s[10:11] offset:-256 sc1
	s_mov_b64 s[16:17], 0
	s_waitcnt vmcnt(0)
	v_cmp_lt_u32_e32 vcc, v1, v2
	s_and_saveexec_b64 s[14:15], vcc
	s_cbranch_execz .LBB0_876
	s_add_u32 s12, s18, 0x32d0200
	s_addc_u32 s13, s19, 0
	s_mov_b32 s0, 1
	s_branch .LBB0_869

.LBB0_873:
	global_load_dword v1, v0, s[10:11] offset:-256 sc1
	s_add_i32 s0, s0, 1
	s_mov_b64 s[24:25], -1
	s_waitcnt vmcnt(0)
	v_cmp_ge_u32_e32 vcc, v1, v2
	s_orn2_b64 s[30:31], vcc, exec
	s_branch .LBB0_868

.LBB0_938:
	s_or_b64 exec, exec, s[12:13]
	v_cvt_f32_u32_e32 v4, v2
	s_waitcnt vmcnt(0)
	v_readfirstlane_b32 s0, v3
	v_sub_u32_e32 v3, 0, v2
	v_rcp_iflag_f32_e32 v4, v4
	v_add_u32_e32 v5, s0, v1
	v_mul_f32_e32 v4, 0x4f7ffffe, v4
	v_cvt_u32_f32_e32 v4, v4
	v_mul_lo_u32 v1, v3, v4
	v_mul_hi_u32 v1, v4, v1
	v_add_u32_e32 v1, v4, v1
	v_mul_hi_u32 v1, v5, v1
	v_mul_lo_u32 v3, v1, v2
	v_sub_u32_e32 v3, v5, v3
	v_add_u32_e32 v4, 1, v1
	v_cmp_ge_u32_e32 vcc, v3, v2
	s_nop 1
	v_cndmask_b32_e32 v1, v1, v4, vcc
	v_sub_u32_e32 v4, v3, v2
	v_cndmask_b32_e32 v3, v3, v4, vcc
	v_add_u32_e32 v4, 1, v1
	v_cmp_ge_u32_e32 vcc, v3, v2
	v_add_u32_e32 v3, 1, v5
	s_nop 0
	v_cndmask_b32_e32 v1, v1, v4, vcc
	v_mul_lo_u32 v4, v2, v1
	v_add_u32_e32 v2, v4, v2
	v_cmp_ne_u32_e32 vcc, v3, v2
	s_and_saveexec_b64 s[0:1], vcc
	s_xor_b64 s[10:11], exec, s[0:1]
	s_cbranch_execz .LBB0_952
	s_waitcnt lgkmcnt(0)
	v_add_u32_e32 v1, 1, v1
	v_mul_lo_u32 v1, v1, v0
	s_add_u32 s18, s14, 0x32d3400
	s_addc_u32 s19, s15, 0
	v_mov_b32_e32 v0, 0
	global_load_dword v0, v0, s[18:19] sc1
	s_waitcnt vmcnt(0)
	v_cmp_lt_u32_e32 vcc, v0, v1
	s_and_saveexec_b64 s[12:13], vcc
	s_cbranch_execz .LBB0_951
	s_add_u32 s16, s14, 0x32d0200
	s_addc_u32 s17, s15, 0
	s_mov_b32 s0, 1
	s_mov_b64 s[24:25], 0
	v_mov_b32_e32 v0, 0
	s_branch .LBB0_942

.LBB0_946:
	global_load_dword v2, v0, s[18:19] sc1
	s_add_i32 s0, s0, 1
	s_mov_b64 s[36:37], -1
	s_waitcnt vmcnt(0)
	v_cmp_ge_u32_e32 vcc, v2, v1
	s_orn2_b64 s[30:31], vcc, exec
	s_branch .LBB0_941

.LBB0_955:
	s_or_b64 exec, exec, s[12:13]
	v_cvt_f32_u32_e32 v3, v0
	s_waitcnt vmcnt(0)
	v_readfirstlane_b32 s0, v2
	s_add_u32 s12, s14, 0x32d3500
	s_addc_u32 s13, s15, 0
	v_rcp_iflag_f32_e32 v3, v3
	v_add_u32_e32 v1, s0, v1
	v_add_u32_e32 v4, 1, v1
	s_mov_b64 s[16:17], -1
	v_mul_f32_e32 v2, 0x4f7ffffe, v3
	v_cvt_u32_f32_e32 v2, v2
	v_sub_u32_e32 v3, 0, v0
	v_mul_lo_u32 v3, v3, v2
	v_mul_hi_u32 v3, v2, v3
	v_add_u32_e32 v2, v2, v3
	v_mul_hi_u32 v2, v1, v2
	v_mul_lo_u32 v3, v2, v0
	v_sub_u32_e32 v1, v1, v3
	v_add_u32_e32 v5, 1, v2
	v_cmp_ge_u32_e32 vcc, v1, v0
	v_sub_u32_e32 v3, v1, v0
	s_nop 0
	v_cndmask_b32_e32 v2, v2, v5, vcc
	v_cndmask_b32_e32 v1, v1, v3, vcc
	v_add_u32_e32 v3, 1, v2
	v_cmp_ge_u32_e32 vcc, v1, v0
	s_nop 1
	v_cndmask_b32_e32 v2, v2, v3, vcc
	v_mul_lo_u32 v1, v0, v2
	v_add_u32_e32 v0, v1, v0
	v_cmp_ne_u32_e32 vcc, v4, v0
	v_mov_b32_e32 v2, v0
	v_mov_b64_e32 v[0:1], s[12:13]
	s_and_saveexec_b64 s[10:11], vcc
	s_cbranch_execz .LBB0_967
	v_mov_b32_e32 v0, 0
	global_load_dword v1, v0, s[12:13] offset:-256 sc1
	s_mov_b64 s[24:25], 0
	s_waitcnt vmcnt(0)
	v_cmp_lt_u32_e32 vcc, v1, v2
	s_and_saveexec_b64 s[18:19], vcc
	s_cbranch_execz .LBB0_966
	s_add_u32 s16, s14, 0x32d0200
	s_addc_u32 s17, s15, 0
	s_mov_b32 s0, 1
	s_mov_b64 s[14:15], 0
	s_branch .LBB0_959

.LBB0_963:
	global_load_dword v1, v0, s[12:13] offset:-256 sc1
	s_add_i32 s0, s0, 1
	s_mov_b64 s[26:27], -1
	s_waitcnt vmcnt(0)
	v_cmp_ge_u32_e32 vcc, v1, v2
	s_orn2_b64 s[36:37], vcc, exec
	s_branch .LBB0_958

.LBB0_1010:
	s_or_b64 exec, exec, s[16:17]
	v_cvt_f32_u32_e32 v4, v2
	s_waitcnt vmcnt(0)
	v_readfirstlane_b32 s0, v3
	v_sub_u32_e32 v3, 0, v2
	v_rcp_iflag_f32_e32 v4, v4
	v_add_u32_e32 v5, s0, v1
	v_mul_f32_e32 v4, 0x4f7ffffe, v4
	v_cvt_u32_f32_e32 v4, v4
	v_mul_lo_u32 v1, v3, v4
	v_mul_hi_u32 v1, v4, v1
	v_add_u32_e32 v1, v4, v1
	v_mul_hi_u32 v1, v5, v1
	v_mul_lo_u32 v3, v1, v2
	v_sub_u32_e32 v3, v5, v3
	v_add_u32_e32 v4, 1, v1
	v_cmp_ge_u32_e32 vcc, v3, v2
	s_nop 1
	v_cndmask_b32_e32 v1, v1, v4, vcc
	v_sub_u32_e32 v4, v3, v2
	v_cndmask_b32_e32 v3, v3, v4, vcc
	v_add_u32_e32 v4, 1, v1
	v_cmp_ge_u32_e32 vcc, v3, v2
	v_add_u32_e32 v3, 1, v5
	s_nop 0
	v_cndmask_b32_e32 v1, v1, v4, vcc
	v_mul_lo_u32 v4, v2, v1
	v_add_u32_e32 v2, v4, v2
	v_cmp_ne_u32_e32 vcc, v3, v2
	s_and_saveexec_b64 s[0:1], vcc
	s_xor_b64 s[12:13], exec, s[0:1]
	s_cbranch_execz .LBB0_1024
	s_waitcnt lgkmcnt(0)
	v_add_u32_e32 v1, 1, v1
	v_mul_lo_u32 v1, v1, v0
	s_add_u32 s24, s14, 0x32d3400
	s_addc_u32 s25, s15, 0
	v_mov_b32_e32 v0, 0
	global_load_dword v0, v0, s[24:25] sc1
	s_waitcnt vmcnt(0)
	v_cmp_lt_u32_e32 vcc, v0, v1
	s_and_saveexec_b64 s[16:17], vcc
	s_cbranch_execz .LBB0_1023
	s_add_u32 s18, s14, 0x32d0200
	s_addc_u32 s19, s15, 0
	s_mov_b32 s0, 1
	s_mov_b64 s[26:27], 0
	v_mov_b32_e32 v0, 0
	s_branch .LBB0_1014

.LBB0_1018:
	global_load_dword v2, v0, s[24:25] sc1
	s_add_i32 s0, s0, 1
	s_mov_b64 s[36:37], -1
	s_waitcnt vmcnt(0)
	v_cmp_ge_u32_e32 vcc, v2, v1
	s_orn2_b64 s[30:31], vcc, exec
	s_branch .LBB0_1013

.LBB0_1027:
	s_or_b64 exec, exec, s[16:17]
	v_cvt_f32_u32_e32 v3, v0
	s_waitcnt vmcnt(0)
	v_readfirstlane_b32 s0, v2
	s_add_u32 s16, s14, 0x32d3500
	s_addc_u32 s17, s15, 0
	v_rcp_iflag_f32_e32 v3, v3
	v_add_u32_e32 v1, s0, v1
	v_add_u32_e32 v4, 1, v1
	s_mov_b64 s[18:19], -1
	v_mul_f32_e32 v2, 0x4f7ffffe, v3
	v_cvt_u32_f32_e32 v2, v2
	v_sub_u32_e32 v3, 0, v0
	v_mul_lo_u32 v3, v3, v2
	v_mul_hi_u32 v3, v2, v3
	v_add_u32_e32 v2, v2, v3
	v_mul_hi_u32 v2, v1, v2
	v_mul_lo_u32 v3, v2, v0
	v_sub_u32_e32 v1, v1, v3
	v_add_u32_e32 v5, 1, v2
	v_cmp_ge_u32_e32 vcc, v1, v0
	v_sub_u32_e32 v3, v1, v0
	s_nop 0
	v_cndmask_b32_e32 v2, v2, v5, vcc
	v_cndmask_b32_e32 v1, v1, v3, vcc
	v_add_u32_e32 v3, 1, v2
	v_cmp_ge_u32_e32 vcc, v1, v0
	s_nop 1
	v_cndmask_b32_e32 v2, v2, v3, vcc
	v_mul_lo_u32 v1, v0, v2
	v_add_u32_e32 v0, v1, v0
	v_cmp_ne_u32_e32 vcc, v4, v0
	v_mov_b32_e32 v2, v0
	v_mov_b64_e32 v[0:1], s[16:17]
	s_and_saveexec_b64 s[12:13], vcc
	s_cbranch_execz .LBB0_1039
	v_mov_b32_e32 v0, 0
	global_load_dword v1, v0, s[16:17] offset:-256 sc1
	s_mov_b64 s[26:27], 0
	s_waitcnt vmcnt(0)
	v_cmp_lt_u32_e32 vcc, v1, v2
	s_and_saveexec_b64 s[24:25], vcc
	s_cbranch_execz .LBB0_1038
	s_add_u32 s18, s14, 0x32d0200
	s_addc_u32 s19, s15, 0
	s_mov_b32 s0, 1
	s_mov_b64 s[14:15], 0
	s_branch .LBB0_1031

.LBB0_1035:
	global_load_dword v1, v0, s[16:17] offset:-256 sc1
	s_add_i32 s0, s0, 1
	s_mov_b64 s[28:29], -1
	s_waitcnt vmcnt(0)
	v_cmp_ge_u32_e32 vcc, v1, v2
	s_orn2_b64 s[36:37], vcc, exec
	s_branch .LBB0_1030

.LBB0_1100:
	s_or_b64 exec, exec, s[16:17]
	v_cvt_f32_u32_e32 v4, v2
	s_waitcnt vmcnt(0)
	v_readfirstlane_b32 s0, v3
	v_sub_u32_e32 v3, 0, v2
	v_rcp_iflag_f32_e32 v4, v4
	v_add_u32_e32 v5, s0, v1
	v_mul_f32_e32 v4, 0x4f7ffffe, v4
	v_cvt_u32_f32_e32 v4, v4
	v_mul_lo_u32 v1, v3, v4
	v_mul_hi_u32 v1, v4, v1
	v_add_u32_e32 v1, v4, v1
	v_mul_hi_u32 v1, v5, v1
	v_mul_lo_u32 v3, v1, v2
	v_sub_u32_e32 v3, v5, v3
	v_add_u32_e32 v4, 1, v1
	v_cmp_ge_u32_e32 vcc, v3, v2
	s_nop 1
	v_cndmask_b32_e32 v1, v1, v4, vcc
	v_sub_u32_e32 v4, v3, v2
	v_cndmask_b32_e32 v3, v3, v4, vcc
	v_add_u32_e32 v4, 1, v1
	v_cmp_ge_u32_e32 vcc, v3, v2
	v_add_u32_e32 v3, 1, v5
	s_nop 0
	v_cndmask_b32_e32 v1, v1, v4, vcc
	v_mul_lo_u32 v4, v2, v1
	v_add_u32_e32 v2, v4, v2
	v_cmp_ne_u32_e32 vcc, v3, v2
	s_and_saveexec_b64 s[0:1], vcc
	s_xor_b64 s[14:15], exec, s[0:1]
	s_cbranch_execz .LBB0_1114
	s_waitcnt lgkmcnt(0)
	v_add_u32_e32 v1, 1, v1
	v_mul_lo_u32 v1, v1, v0
	s_add_u32 s24, s12, 0x32d3400
	s_addc_u32 s25, s13, 0
	v_mov_b32_e32 v0, 0
	global_load_dword v0, v0, s[24:25] sc1
	s_waitcnt vmcnt(0)
	v_cmp_lt_u32_e32 vcc, v0, v1
	s_and_saveexec_b64 s[16:17], vcc
	s_cbranch_execz .LBB0_1113
	s_add_u32 s18, s12, 0x32d0200
	s_addc_u32 s19, s13, 0
	s_mov_b32 s0, 1
	s_mov_b64 s[26:27], 0
	v_mov_b32_e32 v0, 0
	s_branch .LBB0_1104

.LBB0_1117:
	s_or_b64 exec, exec, s[16:17]
	v_cvt_f32_u32_e32 v3, v0
	s_waitcnt vmcnt(0)
	v_readfirstlane_b32 s0, v2
	s_add_u32 s16, s12, 0x32d3500
	s_addc_u32 s17, s13, 0
	v_rcp_iflag_f32_e32 v3, v3
	v_add_u32_e32 v1, s0, v1
	v_add_u32_e32 v4, 1, v1
	s_mov_b64 s[18:19], -1
	v_mul_f32_e32 v2, 0x4f7ffffe, v3
	v_cvt_u32_f32_e32 v2, v2
	v_sub_u32_e32 v3, 0, v0
	v_mul_lo_u32 v3, v3, v2
	v_mul_hi_u32 v3, v2, v3
	v_add_u32_e32 v2, v2, v3
	v_mul_hi_u32 v2, v1, v2
	v_mul_lo_u32 v3, v2, v0
	v_sub_u32_e32 v1, v1, v3
	v_add_u32_e32 v5, 1, v2
	v_cmp_ge_u32_e32 vcc, v1, v0
	v_sub_u32_e32 v3, v1, v0
	s_nop 0
	v_cndmask_b32_e32 v2, v2, v5, vcc
	v_cndmask_b32_e32 v1, v1, v3, vcc
	v_add_u32_e32 v3, 1, v2
	v_cmp_ge_u32_e32 vcc, v1, v0
	s_nop 1
	v_cndmask_b32_e32 v2, v2, v3, vcc
	v_mul_lo_u32 v1, v0, v2
	v_add_u32_e32 v0, v1, v0
	v_cmp_ne_u32_e32 vcc, v4, v0
	v_mov_b32_e32 v2, v0
	v_mov_b64_e32 v[0:1], s[16:17]
	s_and_saveexec_b64 s[14:15], vcc
	s_cbranch_execz .LBB0_1129
	v_mov_b32_e32 v0, 0
	global_load_dword v1, v0, s[16:17] offset:-256 sc1
	s_mov_b64 s[26:27], 0
	s_waitcnt vmcnt(0)
	v_cmp_lt_u32_e32 vcc, v1, v2
	s_and_saveexec_b64 s[24:25], vcc
	s_cbranch_execz .LBB0_1128
	s_add_u32 s18, s12, 0x32d0200
	s_addc_u32 s19, s13, 0
	s_mov_b32 s0, 1
	s_mov_b64 s[12:13], 0
	s_branch .LBB0_1121

.LBB0_1392:
	s_or_b64 exec, exec, s[16:17]
	v_cvt_f32_u32_e32 v4, v2
	s_waitcnt vmcnt(0)
	v_readfirstlane_b32 s0, v3
	v_sub_u32_e32 v3, 0, v2
	v_rcp_iflag_f32_e32 v4, v4
	v_add_u32_e32 v5, s0, v1
	v_mul_f32_e32 v4, 0x4f7ffffe, v4
	v_cvt_u32_f32_e32 v4, v4
	v_mul_lo_u32 v1, v3, v4
	v_mul_hi_u32 v1, v4, v1
	v_add_u32_e32 v1, v4, v1
	v_mul_hi_u32 v1, v5, v1
	v_mul_lo_u32 v3, v1, v2
	v_sub_u32_e32 v3, v5, v3
	v_add_u32_e32 v4, 1, v1
	v_cmp_ge_u32_e32 vcc, v3, v2
	s_nop 1
	v_cndmask_b32_e32 v1, v1, v4, vcc
	v_sub_u32_e32 v4, v3, v2
	v_cndmask_b32_e32 v3, v3, v4, vcc
	v_add_u32_e32 v4, 1, v1
	v_cmp_ge_u32_e32 vcc, v3, v2
	v_add_u32_e32 v3, 1, v5
	s_nop 0
	v_cndmask_b32_e32 v1, v1, v4, vcc
	v_mul_lo_u32 v4, v2, v1
	v_add_u32_e32 v2, v4, v2
	v_cmp_ne_u32_e32 vcc, v3, v2
	s_and_saveexec_b64 s[0:1], vcc
	s_xor_b64 s[14:15], exec, s[0:1]
	s_cbranch_execz .LBB0_1406
	s_waitcnt lgkmcnt(0)
	v_add_u32_e32 v1, 1, v1
	v_mul_lo_u32 v1, v1, v0
	s_add_u32 s26, s18, 0x32d3400
	s_addc_u32 s27, s19, 0
	v_mov_b32_e32 v0, 0
	global_load_dword v0, v0, s[26:27] sc1
	s_waitcnt vmcnt(0)
	v_cmp_lt_u32_e32 vcc, v0, v1
	s_and_saveexec_b64 s[16:17], vcc
	s_cbranch_execz .LBB0_1405
	s_add_u32 s24, s18, 0x32d0200
	s_addc_u32 s25, s19, 0
	s_mov_b32 s0, 1
	s_mov_b64 s[28:29], 0
	v_mov_b32_e32 v0, 0
	s_branch .LBB0_1396

.LBB0_1400:
	global_load_dword v2, v0, s[26:27] sc1
	s_add_i32 s0, s0, 1
	s_mov_b64 s[38:39], -1
	s_waitcnt vmcnt(0)
	v_cmp_ge_u32_e32 vcc, v2, v1
	s_orn2_b64 s[36:37], vcc, exec
	s_branch .LBB0_1395

.LBB0_1409:
	s_or_b64 exec, exec, s[16:17]
	v_cvt_f32_u32_e32 v3, v0
	s_waitcnt vmcnt(0)
	v_readfirstlane_b32 s0, v2
	s_add_u32 s16, s18, 0x32d3500
	s_addc_u32 s17, s19, 0
	v_rcp_iflag_f32_e32 v3, v3
	v_add_u32_e32 v1, s0, v1
	v_add_u32_e32 v4, 1, v1
	s_mov_b64 s[24:25], -1
	v_mul_f32_e32 v2, 0x4f7ffffe, v3
	v_cvt_u32_f32_e32 v2, v2
	v_sub_u32_e32 v3, 0, v0
	v_mul_lo_u32 v3, v3, v2
	v_mul_hi_u32 v3, v2, v3
	v_add_u32_e32 v2, v2, v3
	v_mul_hi_u32 v2, v1, v2
	v_mul_lo_u32 v3, v2, v0
	v_sub_u32_e32 v1, v1, v3
	v_add_u32_e32 v5, 1, v2
	v_cmp_ge_u32_e32 vcc, v1, v0
	v_sub_u32_e32 v3, v1, v0
	s_nop 0
	v_cndmask_b32_e32 v2, v2, v5, vcc
	v_cndmask_b32_e32 v1, v1, v3, vcc
	v_add_u32_e32 v3, 1, v2
	v_cmp_ge_u32_e32 vcc, v1, v0
	s_nop 1
	v_cndmask_b32_e32 v2, v2, v3, vcc
	v_mul_lo_u32 v1, v0, v2
	v_add_u32_e32 v0, v1, v0
	v_cmp_ne_u32_e32 vcc, v4, v0
	v_mov_b32_e32 v2, v0
	v_mov_b64_e32 v[0:1], s[16:17]
	s_and_saveexec_b64 s[14:15], vcc
	s_cbranch_execz .LBB0_1421
	v_mov_b32_e32 v0, 0
	global_load_dword v1, v0, s[16:17] offset:-256 sc1
	s_mov_b64 s[28:29], 0
	s_waitcnt vmcnt(0)
	v_cmp_lt_u32_e32 vcc, v1, v2
	s_and_saveexec_b64 s[26:27], vcc
	s_cbranch_execz .LBB0_1420
	s_add_u32 s24, s18, 0x32d0200
	s_addc_u32 s25, s19, 0
	s_mov_b32 s0, 1
	s_mov_b64 s[18:19], 0
	s_branch .LBB0_1413

.LBB0_1417:
	global_load_dword v1, v0, s[16:17] offset:-256 sc1
	s_add_i32 s0, s0, 1
	s_mov_b64 s[30:31], -1
	s_waitcnt vmcnt(0)
	v_cmp_ge_u32_e32 vcc, v1, v2
	s_orn2_b64 s[38:39], vcc, exec
	s_branch .LBB0_1412

.LBB0_1545:
	global_load_dword v2, v0, s[26:27] sc1
	s_add_i32 s0, s0, 1
	s_mov_b64 s[42:43], -1
	s_waitcnt vmcnt(0)
	v_cmp_ge_u32_e32 vcc, v2, v1
	s_orn2_b64 s[38:39], vcc, exec
	s_branch .LBB0_1540

.LBB0_1562:
	global_load_dword v1, v0, s[16:17] offset:-256 sc1
	s_add_i32 s0, s0, 1
	s_mov_b64 s[30:31], -1
	s_waitcnt vmcnt(0)
	v_cmp_ge_u32_e32 vcc, v1, v2
	s_orn2_b64 s[42:43], vcc, exec
	s_branch .LBB0_1557

.LBB0_1699:
	s_or_b64 exec, exec, s[16:17]
	v_cvt_f32_u32_e32 v4, v2
	s_waitcnt vmcnt(0)
	v_readfirstlane_b32 s1, v3
	v_sub_u32_e32 v3, 0, v2
	v_rcp_iflag_f32_e32 v4, v4
	v_add_u32_e32 v5, s1, v1
	v_mul_f32_e32 v4, 0x4f7ffffe, v4
	v_cvt_u32_f32_e32 v4, v4
	v_mul_lo_u32 v1, v3, v4
	v_mul_hi_u32 v1, v4, v1
	v_add_u32_e32 v1, v4, v1
	v_mul_hi_u32 v1, v5, v1
	v_mul_lo_u32 v3, v1, v2
	v_sub_u32_e32 v3, v5, v3
	v_add_u32_e32 v4, 1, v1
	v_cmp_ge_u32_e32 vcc, v3, v2
	s_nop 1
	v_cndmask_b32_e32 v1, v1, v4, vcc
	v_sub_u32_e32 v4, v3, v2
	v_cndmask_b32_e32 v3, v3, v4, vcc
	v_add_u32_e32 v4, 1, v1
	v_cmp_ge_u32_e32 vcc, v3, v2
	v_add_u32_e32 v3, 1, v5
	s_nop 0
	v_cndmask_b32_e32 v1, v1, v4, vcc
	v_mul_lo_u32 v4, v2, v1
	v_add_u32_e32 v2, v4, v2
	v_cmp_ne_u32_e32 vcc, v3, v2
	s_and_saveexec_b64 s[14:15], vcc
	s_xor_b64 s[14:15], exec, s[14:15]
	s_cbranch_execz .LBB0_1713
	s_waitcnt lgkmcnt(0)
	v_add_u32_e32 v1, 1, v1
	v_mul_lo_u32 v1, v1, v0
	s_add_u32 s24, s30, 0x32d3400
	s_addc_u32 s25, s31, 0
	v_mov_b32_e32 v0, 0
	global_load_dword v0, v0, s[24:25] sc1
	s_waitcnt vmcnt(0)
	v_cmp_lt_u32_e32 vcc, v0, v1
	s_and_saveexec_b64 s[16:17], vcc
	s_cbranch_execz .LBB0_1712
	s_add_u32 s18, s30, 0x32d0200
	s_addc_u32 s19, s31, 0
	s_mov_b32 s1, 1
	s_mov_b64 s[26:27], 0
	v_mov_b32_e32 v0, 0
	s_branch .LBB0_1703

.LBB0_1707:
	global_load_dword v2, v0, s[24:25] sc1
	s_add_i32 s1, s1, 1
	s_mov_b64 s[38:39], -1
	s_waitcnt vmcnt(0)
	v_cmp_ge_u32_e32 vcc, v2, v1
	s_orn2_b64 s[34:35], vcc, exec
	s_branch .LBB0_1702

.LBB0_1716:
	s_or_b64 exec, exec, s[16:17]
	v_cvt_f32_u32_e32 v3, v0
	s_waitcnt vmcnt(0)
	v_readfirstlane_b32 s1, v2
	s_add_u32 s16, s30, 0x32d3500
	s_addc_u32 s17, s31, 0
	v_rcp_iflag_f32_e32 v3, v3
	v_add_u32_e32 v1, s1, v1
	v_add_u32_e32 v4, 1, v1
	s_mov_b64 s[18:19], -1
	v_mul_f32_e32 v2, 0x4f7ffffe, v3
	v_cvt_u32_f32_e32 v2, v2
	v_sub_u32_e32 v3, 0, v0
	v_mul_lo_u32 v3, v3, v2
	v_mul_hi_u32 v3, v2, v3
	v_add_u32_e32 v2, v2, v3
	v_mul_hi_u32 v2, v1, v2
	v_mul_lo_u32 v3, v2, v0
	v_sub_u32_e32 v1, v1, v3
	v_add_u32_e32 v5, 1, v2
	v_cmp_ge_u32_e32 vcc, v1, v0
	v_sub_u32_e32 v3, v1, v0
	s_nop 0
	v_cndmask_b32_e32 v2, v2, v5, vcc
	v_cndmask_b32_e32 v1, v1, v3, vcc
	v_add_u32_e32 v3, 1, v2
	v_cmp_ge_u32_e32 vcc, v1, v0
	s_nop 1
	v_cndmask_b32_e32 v2, v2, v3, vcc
	v_mul_lo_u32 v1, v0, v2
	v_add_u32_e32 v0, v1, v0
	v_cmp_ne_u32_e32 vcc, v4, v0
	v_mov_b32_e32 v2, v0
	v_mov_b64_e32 v[0:1], s[16:17]
	s_and_saveexec_b64 s[14:15], vcc
	s_cbranch_execz .LBB0_1728
	v_mov_b32_e32 v0, 0
	global_load_dword v1, v0, s[16:17] offset:-256 sc1
	s_mov_b64 s[26:27], 0
	s_waitcnt vmcnt(0)
	v_cmp_lt_u32_e32 vcc, v1, v2
	s_and_saveexec_b64 s[24:25], vcc
	s_cbranch_execz .LBB0_1727
	s_add_u32 s18, s30, 0x32d0200
	s_addc_u32 s19, s31, 0
	s_mov_b32 s1, 1
	s_branch .LBB0_1720

.LBB0_1724:
	global_load_dword v1, v0, s[16:17] offset:-256 sc1
	s_add_i32 s1, s1, 1
	s_mov_b64 s[30:31], -1
	s_waitcnt vmcnt(0)
	v_cmp_ge_u32_e32 vcc, v1, v2
	s_orn2_b64 s[38:39], vcc, exec
	s_branch .LBB0_1719

.LBB0_1842:
	s_or_b64 exec, exec, s[14:15]
	v_cvt_f32_u32_e32 v4, v2
	s_waitcnt vmcnt(0)
	v_readfirstlane_b32 s0, v3
	v_sub_u32_e32 v3, 0, v2
	v_rcp_iflag_f32_e32 v4, v4
	v_add_u32_e32 v5, s0, v1
	v_mul_f32_e32 v4, 0x4f7ffffe, v4
	v_cvt_u32_f32_e32 v4, v4
	v_mul_lo_u32 v1, v3, v4
	v_mul_hi_u32 v1, v4, v1
	v_add_u32_e32 v1, v4, v1
	v_mul_hi_u32 v1, v5, v1
	v_mul_lo_u32 v3, v1, v2
	v_sub_u32_e32 v3, v5, v3
	v_add_u32_e32 v4, 1, v1
	v_cmp_ge_u32_e32 vcc, v3, v2
	s_nop 1
	v_cndmask_b32_e32 v1, v1, v4, vcc
	v_sub_u32_e32 v4, v3, v2
	v_cndmask_b32_e32 v3, v3, v4, vcc
	v_add_u32_e32 v4, 1, v1
	v_cmp_ge_u32_e32 vcc, v3, v2
	v_add_u32_e32 v3, 1, v5
	s_nop 0
	v_cndmask_b32_e32 v1, v1, v4, vcc
	v_mul_lo_u32 v4, v2, v1
	v_add_u32_e32 v2, v4, v2
	v_cmp_ne_u32_e32 vcc, v3, v2
	s_and_saveexec_b64 s[0:1], vcc
	s_xor_b64 s[12:13], exec, s[0:1]
	s_cbranch_execz .LBB0_1856
	s_waitcnt lgkmcnt(0)
	v_add_u32_e32 v1, 1, v1
	v_mul_lo_u32 v1, v1, v0
	s_add_u32 s18, s30, 0x32d3400
	s_addc_u32 s19, s31, 0
	v_mov_b32_e32 v0, 0
	global_load_dword v0, v0, s[18:19] sc1
	s_waitcnt vmcnt(0)
	v_cmp_lt_u32_e32 vcc, v0, v1
	s_and_saveexec_b64 s[14:15], vcc
	s_cbranch_execz .LBB0_1855
	s_add_u32 s16, s30, 0x32d0200
	s_addc_u32 s17, s31, 0
	s_mov_b32 s0, 1
	s_mov_b64 s[24:25], 0
	v_mov_b32_e32 v0, 0
	s_branch .LBB0_1846

.LBB0_1850:
	global_load_dword v2, v0, s[18:19] sc1
	s_add_i32 s0, s0, 1
	s_mov_b64 s[34:35], -1
	s_waitcnt vmcnt(0)
	v_cmp_ge_u32_e32 vcc, v2, v1
	s_orn2_b64 s[28:29], vcc, exec
	s_branch .LBB0_1845

.LBB0_1859:
	s_or_b64 exec, exec, s[14:15]
	v_cvt_f32_u32_e32 v3, v0
	s_waitcnt vmcnt(0)
	v_readfirstlane_b32 s0, v2
	s_add_u32 s14, s30, 0x32d3500
	s_addc_u32 s15, s31, 0
	v_rcp_iflag_f32_e32 v3, v3
	v_add_u32_e32 v1, s0, v1
	v_add_u32_e32 v4, 1, v1
	s_mov_b64 s[16:17], -1
	v_mul_f32_e32 v2, 0x4f7ffffe, v3
	v_cvt_u32_f32_e32 v2, v2
	v_sub_u32_e32 v3, 0, v0
	v_mul_lo_u32 v3, v3, v2
	v_mul_hi_u32 v3, v2, v3
	v_add_u32_e32 v2, v2, v3
	v_mul_hi_u32 v2, v1, v2
	v_mul_lo_u32 v3, v2, v0
	v_sub_u32_e32 v1, v1, v3
	v_add_u32_e32 v5, 1, v2
	v_cmp_ge_u32_e32 vcc, v1, v0
	v_sub_u32_e32 v3, v1, v0
	s_nop 0
	v_cndmask_b32_e32 v2, v2, v5, vcc
	v_cndmask_b32_e32 v1, v1, v3, vcc
	v_add_u32_e32 v3, 1, v2
	v_cmp_ge_u32_e32 vcc, v1, v0
	s_nop 1
	v_cndmask_b32_e32 v2, v2, v3, vcc
	v_mul_lo_u32 v1, v0, v2
	v_add_u32_e32 v0, v1, v0
	v_cmp_ne_u32_e32 vcc, v4, v0
	v_mov_b32_e32 v2, v0
	v_mov_b64_e32 v[0:1], s[14:15]
	s_and_saveexec_b64 s[12:13], vcc
	s_cbranch_execz .LBB0_1871
	v_mov_b32_e32 v0, 0
	global_load_dword v1, v0, s[14:15] offset:-256 sc1
	s_mov_b64 s[24:25], 0
	s_waitcnt vmcnt(0)
	v_cmp_lt_u32_e32 vcc, v1, v2
	s_and_saveexec_b64 s[18:19], vcc
	s_cbranch_execz .LBB0_1870
	s_add_u32 s16, s30, 0x32d0200
	s_addc_u32 s17, s31, 0
	s_mov_b32 s0, 1
	s_branch .LBB0_1863

.LBB0_1867:
	global_load_dword v1, v0, s[14:15] offset:-256 sc1
	s_add_i32 s0, s0, 1
	s_mov_b64 s[28:29], -1
	s_waitcnt vmcnt(0)
	v_cmp_ge_u32_e32 vcc, v1, v2
	s_orn2_b64 s[34:35], vcc, exec
	s_branch .LBB0_1862

.LBB0_1940:
	global_load_dword v2, v0, s[24:25] sc1
	s_add_i32 s0, s0, 1
	s_mov_b64 s[34:35], -1
	s_waitcnt vmcnt(0)
	v_cmp_ge_u32_e32 vcc, v2, v1
	s_orn2_b64 s[30:31], vcc, exec
	s_branch .LBB0_1935

.LBB0_1957:
	global_load_dword v1, v0, s[16:17] offset:-256 sc1
	s_add_i32 s0, s0, 1
	s_mov_b64 s[28:29], -1
	s_waitcnt vmcnt(0)
	v_cmp_ge_u32_e32 vcc, v1, v2
	s_orn2_b64 s[34:35], vcc, exec
	s_branch .LBB0_1952

.LBB0_2004:
	s_or_b64 exec, exec, s[14:15]
	v_cvt_f32_u32_e32 v4, v2
	s_waitcnt vmcnt(0)
	v_readfirstlane_b32 s0, v3
	v_sub_u32_e32 v3, 0, v2
	v_rcp_iflag_f32_e32 v4, v4
	v_add_u32_e32 v5, s0, v1
	v_mul_f32_e32 v4, 0x4f7ffffe, v4
	v_cvt_u32_f32_e32 v4, v4
	v_mul_lo_u32 v1, v3, v4
	v_mul_hi_u32 v1, v4, v1
	v_add_u32_e32 v1, v4, v1
	v_mul_hi_u32 v1, v5, v1
	v_mul_lo_u32 v3, v1, v2
	v_sub_u32_e32 v3, v5, v3
	v_add_u32_e32 v4, 1, v1
	v_cmp_ge_u32_e32 vcc, v3, v2
	s_nop 1
	v_cndmask_b32_e32 v1, v1, v4, vcc
	v_sub_u32_e32 v4, v3, v2
	v_cndmask_b32_e32 v3, v3, v4, vcc
	v_add_u32_e32 v4, 1, v1
	v_cmp_ge_u32_e32 vcc, v3, v2
	v_add_u32_e32 v3, 1, v5
	s_nop 0
	v_cndmask_b32_e32 v1, v1, v4, vcc
	v_mul_lo_u32 v4, v2, v1
	v_add_u32_e32 v2, v4, v2
	v_cmp_ne_u32_e32 vcc, v3, v2
	s_and_saveexec_b64 s[0:1], vcc
	s_xor_b64 s[10:11], exec, s[0:1]
	s_cbranch_execz .LBB0_2018
	s_waitcnt lgkmcnt(0)
	v_add_u32_e32 v1, 1, v1
	v_mul_lo_u32 v1, v1, v0
	s_add_u32 s18, s12, 0x32d3400
	s_addc_u32 s19, s13, 0
	v_mov_b32_e32 v0, 0
	global_load_dword v0, v0, s[18:19] sc1
	s_waitcnt vmcnt(0)
	v_cmp_lt_u32_e32 vcc, v0, v1
	s_and_saveexec_b64 s[14:15], vcc
	s_cbranch_execz .LBB0_2017
	s_add_u32 s16, s12, 0x32d0200
	s_addc_u32 s17, s13, 0
	s_mov_b32 s0, 1
	s_mov_b64 s[24:25], 0
	v_mov_b32_e32 v0, 0
	s_branch .LBB0_2008

.LBB0_2012:
	global_load_dword v2, v0, s[18:19] sc1
	s_add_i32 s0, s0, 1
	s_mov_b64 s[30:31], -1
	s_waitcnt vmcnt(0)
	v_cmp_ge_u32_e32 vcc, v2, v1
	s_orn2_b64 s[28:29], vcc, exec
	s_branch .LBB0_2007

.LBB0_2021:
	s_or_b64 exec, exec, s[14:15]
	v_cvt_f32_u32_e32 v3, v0
	s_waitcnt vmcnt(0)
	v_readfirstlane_b32 s0, v2
	s_add_u32 s14, s12, 0x32d3500
	s_addc_u32 s15, s13, 0
	v_rcp_iflag_f32_e32 v3, v3
	v_add_u32_e32 v1, s0, v1
	v_add_u32_e32 v4, 1, v1
	s_mov_b64 s[16:17], -1
	v_mul_f32_e32 v2, 0x4f7ffffe, v3
	v_cvt_u32_f32_e32 v2, v2
	v_sub_u32_e32 v3, 0, v0
	v_mul_lo_u32 v3, v3, v2
	v_mul_hi_u32 v3, v2, v3
	v_add_u32_e32 v2, v2, v3
	v_mul_hi_u32 v2, v1, v2
	v_mul_lo_u32 v3, v2, v0
	v_sub_u32_e32 v1, v1, v3
	v_add_u32_e32 v5, 1, v2
	v_cmp_ge_u32_e32 vcc, v1, v0
	v_sub_u32_e32 v3, v1, v0
	s_nop 0
	v_cndmask_b32_e32 v2, v2, v5, vcc
	v_cndmask_b32_e32 v1, v1, v3, vcc
	v_add_u32_e32 v3, 1, v2
	v_cmp_ge_u32_e32 vcc, v1, v0
	s_nop 1
	v_cndmask_b32_e32 v2, v2, v3, vcc
	v_mul_lo_u32 v1, v0, v2
	v_add_u32_e32 v0, v1, v0
	v_cmp_ne_u32_e32 vcc, v4, v0
	v_mov_b32_e32 v2, v0
	v_mov_b64_e32 v[0:1], s[14:15]
	s_and_saveexec_b64 s[10:11], vcc
	s_cbranch_execz .LBB0_2033
	v_mov_b32_e32 v0, 0
	global_load_dword v1, v0, s[14:15] offset:-256 sc1
	s_mov_b64 s[24:25], 0
	s_waitcnt vmcnt(0)
	v_cmp_lt_u32_e32 vcc, v1, v2
	s_and_saveexec_b64 s[18:19], vcc
	s_cbranch_execz .LBB0_2032
	s_add_u32 s16, s12, 0x32d0200
	s_addc_u32 s17, s13, 0
	s_mov_b32 s0, 1
	s_mov_b64 s[12:13], 0
	s_branch .LBB0_2025

.LBB0_2029:
	global_load_dword v1, v0, s[14:15] offset:-256 sc1
	s_add_i32 s0, s0, 1
	s_mov_b64 s[26:27], -1
	s_waitcnt vmcnt(0)
	v_cmp_ge_u32_e32 vcc, v1, v2
	s_orn2_b64 s[30:31], vcc, exec
	s_branch .LBB0_2024

.LBB0_2094:
	s_or_b64 exec, exec, s[10:11]
	v_cvt_f32_u32_e32 v4, v2
	s_waitcnt vmcnt(0)
	v_readfirstlane_b32 s0, v3
	v_sub_u32_e32 v3, 0, v2
	v_rcp_iflag_f32_e32 v4, v4
	v_add_u32_e32 v5, s0, v1
	v_mul_f32_e32 v4, 0x4f7ffffe, v4
	v_cvt_u32_f32_e32 v4, v4
	v_mul_lo_u32 v1, v3, v4
	v_mul_hi_u32 v1, v4, v1
	v_add_u32_e32 v1, v4, v1
	v_mul_hi_u32 v1, v5, v1
	v_mul_lo_u32 v3, v1, v2
	v_sub_u32_e32 v3, v5, v3
	v_add_u32_e32 v4, 1, v1
	v_cmp_ge_u32_e32 vcc, v3, v2
	s_nop 1
	v_cndmask_b32_e32 v1, v1, v4, vcc
	v_sub_u32_e32 v4, v3, v2
	v_cndmask_b32_e32 v3, v3, v4, vcc
	v_add_u32_e32 v4, 1, v1
	v_cmp_ge_u32_e32 vcc, v3, v2
	v_add_u32_e32 v3, 1, v5
	s_nop 0
	v_cndmask_b32_e32 v1, v1, v4, vcc
	v_mul_lo_u32 v4, v2, v1
	v_add_u32_e32 v2, v4, v2
	v_cmp_ne_u32_e32 vcc, v3, v2
	s_and_saveexec_b64 s[0:1], vcc
	s_xor_b64 s[6:7], exec, s[0:1]
	s_cbranch_execz .LBB0_2108
	s_waitcnt lgkmcnt(0)
	v_add_u32_e32 v1, 1, v1
	v_mul_lo_u32 v1, v1, v0
	s_add_u32 s14, s8, 0x32d3400
	s_addc_u32 s15, s9, 0
	v_mov_b32_e32 v0, 0
	global_load_dword v0, v0, s[14:15] sc1
	s_waitcnt vmcnt(0)
	v_cmp_lt_u32_e32 vcc, v0, v1
	s_and_saveexec_b64 s[10:11], vcc
	s_cbranch_execz .LBB0_2107
	s_add_u32 s12, s8, 0x32d0200
	s_addc_u32 s13, s9, 0
	s_mov_b32 s0, 1
	s_mov_b64 s[16:17], 0
	v_mov_b32_e32 v0, 0
	s_branch .LBB0_2098

.LBB0_2102:
	global_load_dword v2, v0, s[14:15] sc1
	s_add_i32 s0, s0, 1
	s_mov_b64 s[22:23], -1
	s_waitcnt vmcnt(0)
	v_cmp_ge_u32_e32 vcc, v2, v1
	s_orn2_b64 s[20:21], vcc, exec
	s_branch .LBB0_2097

.LBB0_2111:
	s_or_b64 exec, exec, s[10:11]
	v_cvt_f32_u32_e32 v3, v0
	s_waitcnt vmcnt(0)
	v_readfirstlane_b32 s0, v2
	s_add_u32 s10, s8, 0x32d3500
	s_addc_u32 s11, s9, 0
	v_rcp_iflag_f32_e32 v3, v3
	v_add_u32_e32 v1, s0, v1
	v_add_u32_e32 v4, 1, v1
	s_mov_b64 s[12:13], -1
	v_mul_f32_e32 v2, 0x4f7ffffe, v3
	v_cvt_u32_f32_e32 v2, v2
	v_sub_u32_e32 v3, 0, v0
	v_mul_lo_u32 v3, v3, v2
	v_mul_hi_u32 v3, v2, v3
	v_add_u32_e32 v2, v2, v3
	v_mul_hi_u32 v2, v1, v2
	v_mul_lo_u32 v3, v2, v0
	v_sub_u32_e32 v1, v1, v3
	v_add_u32_e32 v5, 1, v2
	v_cmp_ge_u32_e32 vcc, v1, v0
	v_sub_u32_e32 v3, v1, v0
	s_nop 0
	v_cndmask_b32_e32 v2, v2, v5, vcc
	v_cndmask_b32_e32 v1, v1, v3, vcc
	v_add_u32_e32 v3, 1, v2
	v_cmp_ge_u32_e32 vcc, v1, v0
	s_nop 1
	v_cndmask_b32_e32 v2, v2, v3, vcc
	v_mul_lo_u32 v1, v0, v2
	v_add_u32_e32 v0, v1, v0
	v_cmp_ne_u32_e32 vcc, v4, v0
	v_mov_b32_e32 v2, v0
	v_mov_b64_e32 v[0:1], s[10:11]
	s_and_saveexec_b64 s[6:7], vcc
	s_cbranch_execz .LBB0_2123
	v_mov_b32_e32 v0, 0
	global_load_dword v1, v0, s[10:11] offset:-256 sc1
	s_mov_b64 s[16:17], 0
	s_waitcnt vmcnt(0)
	v_cmp_lt_u32_e32 vcc, v1, v2
	s_and_saveexec_b64 s[14:15], vcc
	s_cbranch_execz .LBB0_2122
	s_add_u32 s12, s8, 0x32d0200
	s_addc_u32 s13, s9, 0
	s_mov_b32 s0, 1
	s_mov_b64 s[8:9], 0
	s_branch .LBB0_2115

.LBB0_2119:
	global_load_dword v1, v0, s[10:11] offset:-256 sc1
	s_add_i32 s0, s0, 1
	s_mov_b64 s[18:19], -1
	s_waitcnt vmcnt(0)
	v_cmp_ge_u32_e32 vcc, v1, v2
	s_orn2_b64 s[22:23], vcc, exec
	s_branch .LBB0_2114
